# second weight-transpose tile kind: 15 row loads issued as a batch, LDS writes behind counted waits
# speedup vs baseline: 1.0155x; 1.0062x over previous
; DI unsigned pk2(float a, float b) { f2_t v = {a, b}; bf2_t r = __builtin_convertvector(v, bf2_t); return __builtin_bit_cast(unsigned, r); }
; DI int TID() { int t = threadIdx.x; asm volatile("" : "+v"(t)); return t; }
; DI void transpose_tile(const float* __restrict__ src, int sld, int k0, int n0, int kind, u16* __restrict__ dst, int dld,
;                        char* ldsraw) {
;   float* t = (float*)ldsraw;
;   const int tid = TID();
;   {
;     const int nn = tid & 63, kq = tid >> 6;
;     const int n = n0 + nn;
;     const int sc = (kind == 0) ? win_srccol(n) : ((kind == 1) ? 6432 + n : n);
; #pragma unroll
;     for (int i = 0; i < 16; ++i) {
;       const int kk = kq * 16 + i;
;       t[kk * 65 + nn] = (sc >= 0) ? src[(size_t)(k0 + kk) * sld + sc] : 0.f;
;     }
;   }
;   __syncthreads();
;   {
;     const int nn = tid >> 2, ks = (tid & 3) * 16;
;     unsigned o[8];
; #pragma unroll
;     for (int i = 0; i < 8; ++i) o[i] = pk2(t[(ks + 2 * i) * 65 + nn], t[(ks + 2 * i + 1) * 65 + nn]);
;     uint4* d = (uint4*)(dst + (size_t)(n0 + nn) * dld + k0 + ks);
;     d[0] = make_uint4(o[0], o[1], o[2], o[3]);
;     d[1] = make_uint4(o[4], o[5], o[6], o[7]);
;   }
;   __syncthreads();
; }
; DI void p0_item(const Params& p, int l, int it, const float* __restrict__ xin, char* lds) {
;     ...
;     } else if (it < 2656) {
;       const int j = it - 1632;
;       transpose_tile(p.w_in + (size_t)l * 1024 * 10528, 10528, (j & 15) * 64, (j >> 4) * 64, 1, WGT(l), 1024, lds);
.LBB0_50:
	s_andn2_b64 vcc, exec, s[0:1]
	s_cbranch_vccnz .LBB0_52
	s_and_b32 s1, s5, 0x3fc0
	v_mov_b32_e32 v10, v209
	s_addk_i32 s1, 0xe680
	v_readlane_b32 s36, v251, 2
	v_and_b32_e32 v2, 63, v10
	v_or_b32_e32 v0, s1, v2
	v_ashrrev_i32_e32 v12, 2, v10
	v_readlane_b32 s40, v251, 6
	v_readlane_b32 s41, v251, 7
	s_and_b32 s0, s6, 0x3c0
	v_and_b32_e32 v3, -16, v12
	v_lshl_add_u64 v[4:5], v[0:1], 2, s[40:41]
	s_mov_b64 s[2:3], 0x2926480
	v_lshl_add_u64 v[4:5], v[4:5], 0, s[2:3]
	v_add_u32_e32 v0, s0, v3
	v_lshlrev_b32_e32 v2, 2, v2
	v_mad_i64_i32 v[6:7], s[2:3], v0, s58, v[4:5]
	global_load_dword v11, v[6:7], off
	s_lshl_b32 s18, s0, 1
	v_readlane_b32 s37, v251, 3
	v_readlane_b32 s38, v251, 4
	v_readlane_b32 s39, v251, 5
	v_readlane_b32 s42, v251, 8
	v_readlane_b32 s43, v251, 9
	v_readlane_b32 s44, v251, 10
	v_readlane_b32 s45, v251, 11
	v_readlane_b32 s46, v251, 12
	v_readlane_b32 s47, v251, 13
	v_readlane_b32 s48, v251, 14
	v_readlane_b32 s49, v251, 15
	v_readlane_b32 s50, v251, 16
	v_readlane_b32 s51, v251, 17
	v_mad_u64_u32 v[6:7], s[2:3], v3, s57, v[2:3]
	v_or_b32_e32 v3, 1, v0
	v_mad_i64_i32 v[8:9], s[2:3], v3, s58, v[4:5]
	global_load_dword v228, v[8:9], off
	v_or_b32_e32 v3, 2, v0
	v_mad_i64_i32 v[8:9], s[2:3], v3, s58, v[4:5]
	global_load_dword v229, v[8:9], off
	v_or_b32_e32 v3, 3, v0
	v_mad_i64_i32 v[8:9], s[2:3], v3, s58, v[4:5]
	global_load_dword v230, v[8:9], off
	v_or_b32_e32 v3, 4, v0
	v_mad_i64_i32 v[8:9], s[2:3], v3, s58, v[4:5]
	global_load_dword v231, v[8:9], off
	v_or_b32_e32 v3, 5, v0
	v_mad_i64_i32 v[8:9], s[2:3], v3, s58, v[4:5]
	global_load_dword v232, v[8:9], off
	v_or_b32_e32 v3, 6, v0
	v_mad_i64_i32 v[8:9], s[2:3], v3, s58, v[4:5]
	global_load_dword v233, v[8:9], off
	v_or_b32_e32 v3, 7, v0
	v_mad_i64_i32 v[8:9], s[2:3], v3, s58, v[4:5]
	global_load_dword v234, v[8:9], off
	v_or_b32_e32 v3, 8, v0
	v_mad_i64_i32 v[8:9], s[2:3], v3, s58, v[4:5]
	global_load_dword v235, v[8:9], off
	v_or_b32_e32 v3, 9, v0
	v_mad_i64_i32 v[8:9], s[2:3], v3, s58, v[4:5]
	global_load_dword v236, v[8:9], off
	v_or_b32_e32 v3, 10, v0
	v_mad_i64_i32 v[8:9], s[2:3], v3, s58, v[4:5]
	global_load_dword v237, v[8:9], off
	v_or_b32_e32 v3, 11, v0
	v_mad_i64_i32 v[8:9], s[2:3], v3, s58, v[4:5]
	global_load_dword v238, v[8:9], off
	v_or_b32_e32 v3, 12, v0
	v_mad_i64_i32 v[8:9], s[2:3], v3, s58, v[4:5]
	global_load_dword v239, v[8:9], off
	v_or_b32_e32 v3, 13, v0
	v_mad_i64_i32 v[8:9], s[2:3], v3, s58, v[4:5]
	global_load_dword v240, v[8:9], off
	v_or_b32_e32 v3, 14, v0
	v_mad_i64_i32 v[8:9], s[2:3], v3, s58, v[4:5]
	global_load_dword v241, v[8:9], off
	s_waitcnt vmcnt(13)
	ds_write2_b32 v6, v11, v228 offset1:65
	s_waitcnt vmcnt(11)
	ds_write2_b32 v6, v229, v230 offset0:130 offset1:195
	v_add_u32_e32 v11, 0x400, v6
	s_waitcnt vmcnt(9)
	ds_write2_b32 v11, v231, v232 offset0:4 offset1:69
	s_waitcnt vmcnt(7)
	ds_write2_b32 v11, v233, v234 offset0:134 offset1:199
	v_add_u32_e32 v11, 0x800, v6
	s_waitcnt vmcnt(5)
	ds_write2_b32 v11, v235, v236 offset0:8 offset1:73
	s_waitcnt vmcnt(3)
	ds_write2_b32 v11, v237, v238 offset0:138 offset1:203
	v_add_u32_e32 v8, 0xc00, v6
	s_waitcnt vmcnt(1)
	ds_write2_b32 v8, v239, v240 offset0:12 offset1:77
	s_waitcnt vmcnt(0)
	ds_write_b32 v6, v241 offset:3640
	v_or_b32_e32 v0, 15, v12
	v_add_u32_e32 v3, s0, v0
	v_mad_i64_i32 v[4:5], s[2:3], v3, s58, v[4:5]
	global_load_dword v4, v[4:5], off
	v_mad_u64_u32 v[2:3], s[2:3], v0, s57, v[2:3]
	v_lshlrev_b32_e32 v0, 4, v10
	v_and_b32_e32 v0, 48, v0
	v_mul_u32_u24_e32 v3, 0x41, v0
	v_readlane_b32 s2, v251, 61
	v_readlane_b32 s3, v251, 62
	v_lshlrev_b32_e32 v0, 1, v0
	s_waitcnt vmcnt(0)
	ds_write_b32 v2, v4
	v_and_b32_e32 v2, -4, v10
	v_lshl_add_u32 v10, v3, 2, v2
	s_waitcnt lgkmcnt(0)
	s_barrier
	ds_read2_b32 v[2:3], v10 offset1:65
	ds_read2_b32 v[4:5], v10 offset0:130 offset1:195
	v_add_u32_e32 v6, 0x400, v10
	v_add_u32_e32 v8, 0x800, v10
	v_add_u32_e32 v10, 0xc00, v10
	s_waitcnt lgkmcnt(1)
	v_cvt_pk_f16_f32 v2, v2, v3
	s_waitcnt lgkmcnt(0)
	v_cvt_pk_f16_f32 v3, v4, v5
	ds_read2_b32 v[4:5], v6 offset0:4 offset1:69
	ds_read2_b32 v[6:7], v6 offset0:134 offset1:199
	s_waitcnt lgkmcnt(1)
	v_cvt_pk_f16_f32 v4, v4, v5
	s_waitcnt lgkmcnt(0)
	v_cvt_pk_f16_f32 v5, v6, v7
	ds_read2_b32 v[6:7], v8 offset0:8 offset1:73
	ds_read2_b32 v[8:9], v8 offset0:138 offset1:203
	s_waitcnt lgkmcnt(1)
	v_cvt_pk_f16_f32 v6, v6, v7
	s_waitcnt lgkmcnt(0)
	v_cvt_pk_f16_f32 v7, v8, v9
	ds_read2_b32 v[8:9], v10 offset0:12 offset1:77
	ds_read2_b32 v[10:11], v10 offset0:142 offset1:207
	s_waitcnt lgkmcnt(1)
	v_cvt_pk_f16_f32 v8, v8, v9
	s_waitcnt lgkmcnt(0)
	v_cvt_pk_f16_f32 v9, v10, v11
	v_add_u32_e32 v10, s1, v12
	v_ashrrev_i32_e32 v11, 31, v10
	v_lshlrev_b64 v[10:11], 11, v[10:11]
	v_lshl_add_u64 v[10:11], s[2:3], 0, v[10:11]
	v_lshl_add_u64 v[10:11], v[10:11], 0, s[18:19]
	v_lshl_add_u64 v[10:11], v[10:11], 0, v[0:1]
	global_store_dwordx4 v[10:11], v[2:5], off
	global_store_dwordx4 v[10:11], v[6:9], off offset:16
	s_barrier

; DI unsigned pk2(float a, float b) { f2_t v = {a, b}; bf2_t r = __builtin_convertvector(v, bf2_t); return __builtin_bit_cast(unsigned, r); }
; DI int TID() { int t = threadIdx.x; asm volatile("" : "+v"(t)); return t; }
; DI void transpose_tile(const float* __restrict__ src, int sld, int k0, int n0, int kind, u16* __restrict__ dst, int dld,
;                        char* ldsraw) {
;   float* t = (float*)ldsraw;
;   const int tid = TID();
;   {
;     const int nn = tid & 63, kq = tid >> 6;
;     const int n = n0 + nn;
;     const int sc = (kind == 0) ? win_srccol(n) : ((kind == 1) ? 6432 + n : n);
; #pragma unroll
;     for (int i = 0; i < 16; ++i) {
;       const int kk = kq * 16 + i;
;       t[kk * 65 + nn] = (sc >= 0) ? src[(size_t)(k0 + kk) * sld + sc] : 0.f;
;     }
;   }
;   __syncthreads();
;   {
;     const int nn = tid >> 2, ks = (tid & 3) * 16;
;     unsigned o[8];
; #pragma unroll
;     for (int i = 0; i < 8; ++i) o[i] = pk2(t[(ks + 2 * i) * 65 + nn], t[(ks + 2 * i + 1) * 65 + nn]);
;     uint4* d = (uint4*)(dst + (size_t)(n0 + nn) * dld + k0 + ks);
;     d[0] = make_uint4(o[0], o[1], o[2], o[3]);
;     d[1] = make_uint4(o[4], o[5], o[6], o[7]);
;   }
;   __syncthreads();
; }
; DI void p0_item(const Params& p, int l, int it, const float* __restrict__ xin, char* lds) {
;     ...
;     } else if (it < 2656) {
;       const int j = it - 1632;
;       transpose_tile(p.w_in + (size_t)l * 1024 * 10528, 10528, (j & 15) * 64, (j >> 4) * 64, 1, WGT(l), 1024, lds);
.LBB0_125:
	s_andn2_b64 vcc, exec, s[0:1]
	s_cbranch_vccnz .LBB0_127
	s_lshl_b32 s1, s5, 2
	s_and_b32 s1, s1, 0x3fc0
	v_mov_b32_e32 v10, v209
	s_addk_i32 s1, 0xe680
	v_readlane_b32 s36, v251, 2
	v_and_b32_e32 v2, 63, v10
	s_lshl_b32 s0, s5, 6
	v_or_b32_e32 v0, s1, v2
	v_ashrrev_i32_e32 v12, 2, v10
	v_readlane_b32 s40, v251, 6
	v_readlane_b32 s41, v251, 7
	s_and_b32 s0, s0, 0x3c0
	v_and_b32_e32 v3, -16, v12
	v_lshl_add_u64 v[4:5], v[0:1], 2, s[40:41]
	s_mov_b64 s[2:3], 0x6480
	v_lshl_add_u64 v[4:5], v[4:5], 0, s[2:3]
	v_add_u32_e32 v0, s0, v3
	v_lshlrev_b32_e32 v2, 2, v2
	v_mad_i64_i32 v[6:7], s[2:3], v0, s58, v[4:5]
	global_load_dword v11, v[6:7], off
	v_readlane_b32 s37, v251, 3
	v_readlane_b32 s38, v251, 4
	v_readlane_b32 s39, v251, 5
	v_readlane_b32 s42, v251, 8
	v_readlane_b32 s43, v251, 9
	v_readlane_b32 s44, v251, 10
	v_readlane_b32 s45, v251, 11
	v_readlane_b32 s46, v251, 12
	v_readlane_b32 s47, v251, 13
	v_readlane_b32 s48, v251, 14
	v_readlane_b32 s49, v251, 15
	v_readlane_b32 s50, v251, 16
	v_readlane_b32 s51, v251, 17
	v_mad_u64_u32 v[6:7], s[2:3], v3, s57, v[2:3]
	v_or_b32_e32 v3, 1, v0
	v_mad_i64_i32 v[8:9], s[2:3], v3, s58, v[4:5]
	global_load_dword v228, v[8:9], off
	v_or_b32_e32 v3, 2, v0
	v_mad_i64_i32 v[8:9], s[2:3], v3, s58, v[4:5]
	global_load_dword v229, v[8:9], off
	v_or_b32_e32 v3, 3, v0
	v_mad_i64_i32 v[8:9], s[2:3], v3, s58, v[4:5]
	global_load_dword v230, v[8:9], off
	v_or_b32_e32 v3, 4, v0
	v_mad_i64_i32 v[8:9], s[2:3], v3, s58, v[4:5]
	global_load_dword v231, v[8:9], off
	v_or_b32_e32 v3, 5, v0
	v_mad_i64_i32 v[8:9], s[2:3], v3, s58, v[4:5]
	global_load_dword v232, v[8:9], off
	v_or_b32_e32 v3, 6, v0
	v_mad_i64_i32 v[8:9], s[2:3], v3, s58, v[4:5]
	global_load_dword v233, v[8:9], off
	v_or_b32_e32 v3, 7, v0
	v_mad_i64_i32 v[8:9], s[2:3], v3, s58, v[4:5]
	global_load_dword v234, v[8:9], off
	v_or_b32_e32 v3, 8, v0
	v_mad_i64_i32 v[8:9], s[2:3], v3, s58, v[4:5]
	global_load_dword v235, v[8:9], off
	v_or_b32_e32 v3, 9, v0
	v_mad_i64_i32 v[8:9], s[2:3], v3, s58, v[4:5]
	global_load_dword v236, v[8:9], off
	v_or_b32_e32 v3, 10, v0
	v_mad_i64_i32 v[8:9], s[2:3], v3, s58, v[4:5]
	global_load_dword v237, v[8:9], off
	v_or_b32_e32 v3, 11, v0
	v_mad_i64_i32 v[8:9], s[2:3], v3, s58, v[4:5]
	global_load_dword v238, v[8:9], off
	v_or_b32_e32 v3, 12, v0
	v_mad_i64_i32 v[8:9], s[2:3], v3, s58, v[4:5]
	global_load_dword v239, v[8:9], off
	v_or_b32_e32 v3, 13, v0
	v_mad_i64_i32 v[8:9], s[2:3], v3, s58, v[4:5]
	global_load_dword v240, v[8:9], off
	v_or_b32_e32 v3, 14, v0
	v_mad_i64_i32 v[8:9], s[2:3], v3, s58, v[4:5]
	global_load_dword v241, v[8:9], off
	s_waitcnt vmcnt(13)
	ds_write2_b32 v6, v11, v228 offset1:65
	s_waitcnt vmcnt(11)
	ds_write2_b32 v6, v229, v230 offset0:130 offset1:195
	v_add_u32_e32 v11, 0x400, v6
	s_waitcnt vmcnt(9)
	ds_write2_b32 v11, v231, v232 offset0:4 offset1:69
	s_waitcnt vmcnt(7)
	ds_write2_b32 v11, v233, v234 offset0:134 offset1:199
	v_add_u32_e32 v11, 0x800, v6
	s_waitcnt vmcnt(5)
	ds_write2_b32 v11, v235, v236 offset0:8 offset1:73
	s_waitcnt vmcnt(3)
	ds_write2_b32 v11, v237, v238 offset0:138 offset1:203
	v_add_u32_e32 v8, 0xc00, v6
	s_waitcnt vmcnt(1)
	ds_write2_b32 v8, v239, v240 offset0:12 offset1:77
	s_waitcnt vmcnt(0)
	ds_write_b32 v6, v241 offset:3640
	v_or_b32_e32 v0, 15, v12
	v_add_u32_e32 v3, s0, v0
	v_mad_i64_i32 v[4:5], s[2:3], v3, s58, v[4:5]
	global_load_dword v4, v[4:5], off
	v_mad_u64_u32 v[2:3], s[2:3], v0, s57, v[2:3]
	v_lshlrev_b32_e32 v0, 4, v10
	v_and_b32_e32 v0, 48, v0
	v_mul_u32_u24_e32 v3, 0x41, v0
	v_lshlrev_b32_e32 v0, 1, v0
	s_waitcnt vmcnt(0)
	ds_write_b32 v2, v4
	v_and_b32_e32 v2, -4, v10
	v_lshl_add_u32 v10, v3, 2, v2
	s_waitcnt lgkmcnt(0)
	s_barrier
	ds_read2_b32 v[2:3], v10 offset1:65
	ds_read2_b32 v[4:5], v10 offset0:130 offset1:195
	v_add_u32_e32 v6, 0x400, v10
	v_add_u32_e32 v8, 0x800, v10
	v_add_u32_e32 v10, 0xc00, v10
	s_waitcnt lgkmcnt(1)
	v_cvt_pk_f16_f32 v2, v2, v3
	s_waitcnt lgkmcnt(0)
	v_cvt_pk_f16_f32 v3, v4, v5
	ds_read2_b32 v[4:5], v6 offset0:4 offset1:69
	ds_read2_b32 v[6:7], v6 offset0:134 offset1:199
	s_waitcnt lgkmcnt(1)
	v_cvt_pk_f16_f32 v4, v4, v5
	s_waitcnt lgkmcnt(0)
	v_cvt_pk_f16_f32 v5, v6, v7
	ds_read2_b32 v[6:7], v8 offset0:8 offset1:73
	ds_read2_b32 v[8:9], v8 offset0:138 offset1:203
	s_waitcnt lgkmcnt(1)
	v_cvt_pk_f16_f32 v6, v6, v7
	s_waitcnt lgkmcnt(0)
	v_cvt_pk_f16_f32 v7, v8, v9
	ds_read2_b32 v[8:9], v10 offset0:12 offset1:77
	ds_read2_b32 v[10:11], v10 offset0:142 offset1:207
	s_waitcnt lgkmcnt(1)
	v_cvt_pk_f16_f32 v8, v8, v9
	s_waitcnt lgkmcnt(0)
	v_cvt_pk_f16_f32 v9, v10, v11
	v_add_u32_e32 v10, s1, v12
	v_ashrrev_i32_e32 v11, 31, v10
	s_mov_b32 s1, s19
	v_readlane_b32 s8, v253, 12
	v_lshlrev_b64 v[10:11], 11, v[10:11]
	v_readlane_b32 s18, v253, 22
	v_readlane_b32 s19, v253, 23
	v_readlane_b32 s20, v253, 24
	v_readlane_b32 s21, v253, 25
	s_mov_b32 s19, s1
	s_lshl_b32 s18, s0, 1
	v_lshl_add_u64 v[10:11], s[20:21], 0, v[10:11]
	v_lshl_add_u64 v[10:11], v[10:11], 0, s[18:19]
	v_lshl_add_u64 v[10:11], v[10:11], 0, v[0:1]
	v_readlane_b32 s9, v253, 13
	v_readlane_b32 s10, v253, 14
	v_readlane_b32 s11, v253, 15
	v_readlane_b32 s12, v253, 16
	v_readlane_b32 s13, v253, 17
	v_readlane_b32 s14, v253, 18
	v_readlane_b32 s15, v253, 19
	v_readlane_b32 s16, v253, 20
	v_readlane_b32 s17, v253, 21
	v_readlane_b32 s22, v253, 26
	v_readlane_b32 s23, v253, 27
	global_store_dwordx4 v[10:11], v[2:5], off
	global_store_dwordx4 v[10:11], v[6:9], off offset:16
	s_barrier

; DI unsigned pk2(float a, float b) { f2_t v = {a, b}; bf2_t r = __builtin_convertvector(v, bf2_t); return __builtin_bit_cast(unsigned, r); }
; DI int TID() { int t = threadIdx.x; asm volatile("" : "+v"(t)); return t; }
; DI void transpose_tile(const float* __restrict__ src, int sld, int k0, int n0, int kind, u16* __restrict__ dst, int dld,
;                        char* ldsraw) {
;   float* t = (float*)ldsraw;
;   const int tid = TID();
;   {
;     const int nn = tid & 63, kq = tid >> 6;
;     const int n = n0 + nn;
;     const int sc = (kind == 0) ? win_srccol(n) : ((kind == 1) ? 6432 + n : n);
; #pragma unroll
;     for (int i = 0; i < 16; ++i) {
;       const int kk = kq * 16 + i;
;       t[kk * 65 + nn] = (sc >= 0) ? src[(size_t)(k0 + kk) * sld + sc] : 0.f;
;     }
;   }
;   __syncthreads();
;   {
;     const int nn = tid >> 2, ks = (tid & 3) * 16;
;     unsigned o[8];
; #pragma unroll
;     for (int i = 0; i < 8; ++i) o[i] = pk2(t[(ks + 2 * i) * 65 + nn], t[(ks + 2 * i + 1) * 65 + nn]);
;     uint4* d = (uint4*)(dst + (size_t)(n0 + nn) * dld + k0 + ks);
;     d[0] = make_uint4(o[0], o[1], o[2], o[3]);
;     d[1] = make_uint4(o[4], o[5], o[6], o[7]);
;   }
;   __syncthreads();
; }
; DI void p0_item(const Params& p, int l, int it, const float* __restrict__ xin, char* lds) {
;     ...
;     } else if (it < 2656) {
;       const int j = it - 1632;
;       transpose_tile(p.w_in + (size_t)l * 1024 * 10528, 10528, (j & 15) * 64, (j >> 4) * 64, 1, WGT(l), 1024, lds);
.LBB0_537:
	s_andn2_b64 vcc, exec, s[0:1]
	s_cbranch_vccnz .LBB0_539
	s_lshl_b32 s1, s4, 2
	s_and_b32 s1, s1, 0x3fc0
	v_mov_b32_e32 v10, v209
	s_addk_i32 s1, 0xe680
	v_readlane_b32 s36, v251, 2
	v_and_b32_e32 v2, 63, v10
	s_lshl_b32 s0, s4, 6
	v_or_b32_e32 v0, s1, v2
	v_ashrrev_i32_e32 v12, 2, v10
	v_readlane_b32 s40, v251, 6
	v_readlane_b32 s41, v251, 7
	s_and_b32 s0, s0, 0x3c0
	v_and_b32_e32 v3, -16, v12
	v_lshl_add_u64 v[4:5], v[0:1], 2, s[40:41]
	s_mov_b64 s[2:3], 0x2926480
	v_lshl_add_u64 v[4:5], v[4:5], 0, s[2:3]
	v_add_u32_e32 v0, s0, v3
	v_lshlrev_b32_e32 v2, 2, v2
	v_mad_i64_i32 v[6:7], s[2:3], v0, s58, v[4:5]
	global_load_dword v11, v[6:7], off
	s_lshl_b32 s18, s0, 1
	v_readlane_b32 s37, v251, 3
	v_readlane_b32 s38, v251, 4
	v_readlane_b32 s39, v251, 5
	v_readlane_b32 s42, v251, 8
	v_readlane_b32 s43, v251, 9
	v_readlane_b32 s44, v251, 10
	v_readlane_b32 s45, v251, 11
	v_readlane_b32 s46, v251, 12
	v_readlane_b32 s47, v251, 13
	v_readlane_b32 s48, v251, 14
	v_readlane_b32 s49, v251, 15
	v_readlane_b32 s50, v251, 16
	v_readlane_b32 s51, v251, 17
	v_mad_u64_u32 v[6:7], s[2:3], v3, s57, v[2:3]
	v_or_b32_e32 v3, 1, v0
	v_mad_i64_i32 v[8:9], s[2:3], v3, s58, v[4:5]
	global_load_dword v228, v[8:9], off
	v_or_b32_e32 v3, 2, v0
	v_mad_i64_i32 v[8:9], s[2:3], v3, s58, v[4:5]
	global_load_dword v229, v[8:9], off
	v_or_b32_e32 v3, 3, v0
	v_mad_i64_i32 v[8:9], s[2:3], v3, s58, v[4:5]
	global_load_dword v230, v[8:9], off
	v_or_b32_e32 v3, 4, v0
	v_mad_i64_i32 v[8:9], s[2:3], v3, s58, v[4:5]
	global_load_dword v231, v[8:9], off
	v_or_b32_e32 v3, 5, v0
	v_mad_i64_i32 v[8:9], s[2:3], v3, s58, v[4:5]
	global_load_dword v232, v[8:9], off
	v_or_b32_e32 v3, 6, v0
	v_mad_i64_i32 v[8:9], s[2:3], v3, s58, v[4:5]
	global_load_dword v233, v[8:9], off
	v_or_b32_e32 v3, 7, v0
	v_mad_i64_i32 v[8:9], s[2:3], v3, s58, v[4:5]
	global_load_dword v234, v[8:9], off
	v_or_b32_e32 v3, 8, v0
	v_mad_i64_i32 v[8:9], s[2:3], v3, s58, v[4:5]
	global_load_dword v235, v[8:9], off
	v_or_b32_e32 v3, 9, v0
	v_mad_i64_i32 v[8:9], s[2:3], v3, s58, v[4:5]
	global_load_dword v236, v[8:9], off
	v_or_b32_e32 v3, 10, v0
	v_mad_i64_i32 v[8:9], s[2:3], v3, s58, v[4:5]
	global_load_dword v237, v[8:9], off
	v_or_b32_e32 v3, 11, v0
	v_mad_i64_i32 v[8:9], s[2:3], v3, s58, v[4:5]
	global_load_dword v238, v[8:9], off
	v_or_b32_e32 v3, 12, v0
	v_mad_i64_i32 v[8:9], s[2:3], v3, s58, v[4:5]
	global_load_dword v239, v[8:9], off
	v_or_b32_e32 v3, 13, v0
	v_mad_i64_i32 v[8:9], s[2:3], v3, s58, v[4:5]
	global_load_dword v240, v[8:9], off
	v_or_b32_e32 v3, 14, v0
	v_mad_i64_i32 v[8:9], s[2:3], v3, s58, v[4:5]
	global_load_dword v241, v[8:9], off
	s_waitcnt vmcnt(13)
	ds_write2_b32 v6, v11, v228 offset1:65
	s_waitcnt vmcnt(11)
	ds_write2_b32 v6, v229, v230 offset0:130 offset1:195
	v_add_u32_e32 v11, 0x400, v6
	s_waitcnt vmcnt(9)
	ds_write2_b32 v11, v231, v232 offset0:4 offset1:69
	s_waitcnt vmcnt(7)
	ds_write2_b32 v11, v233, v234 offset0:134 offset1:199
	v_add_u32_e32 v11, 0x800, v6
	s_waitcnt vmcnt(5)
	ds_write2_b32 v11, v235, v236 offset0:8 offset1:73
	s_waitcnt vmcnt(3)
	ds_write2_b32 v11, v237, v238 offset0:138 offset1:203
	v_add_u32_e32 v8, 0xc00, v6
	s_waitcnt vmcnt(1)
	ds_write2_b32 v8, v239, v240 offset0:12 offset1:77
	s_waitcnt vmcnt(0)
	ds_write_b32 v6, v241 offset:3640
	v_or_b32_e32 v0, 15, v12
	v_add_u32_e32 v3, s0, v0
	v_mad_i64_i32 v[4:5], s[2:3], v3, s58, v[4:5]
	global_load_dword v4, v[4:5], off
	v_mad_u64_u32 v[2:3], s[2:3], v0, s57, v[2:3]
	v_lshlrev_b32_e32 v0, 4, v10
	v_and_b32_e32 v0, 48, v0
	v_mul_u32_u24_e32 v3, 0x41, v0
	v_readlane_b32 s2, v251, 61
	v_readlane_b32 s3, v251, 62
	v_lshlrev_b32_e32 v0, 1, v0
	s_waitcnt vmcnt(0)
	ds_write_b32 v2, v4
	v_and_b32_e32 v2, -4, v10
	v_lshl_add_u32 v10, v3, 2, v2
	s_waitcnt lgkmcnt(0)
	s_barrier
	ds_read2_b32 v[2:3], v10 offset1:65
	ds_read2_b32 v[4:5], v10 offset0:130 offset1:195
	v_add_u32_e32 v6, 0x400, v10
	v_add_u32_e32 v8, 0x800, v10
	v_add_u32_e32 v10, 0xc00, v10
	s_waitcnt lgkmcnt(1)
	v_cvt_pk_f16_f32 v2, v2, v3
	s_waitcnt lgkmcnt(0)
	v_cvt_pk_f16_f32 v3, v4, v5
	ds_read2_b32 v[4:5], v6 offset0:4 offset1:69
	ds_read2_b32 v[6:7], v6 offset0:134 offset1:199
	s_waitcnt lgkmcnt(1)
	v_cvt_pk_f16_f32 v4, v4, v5
	s_waitcnt lgkmcnt(0)
	v_cvt_pk_f16_f32 v5, v6, v7
	ds_read2_b32 v[6:7], v8 offset0:8 offset1:73
	ds_read2_b32 v[8:9], v8 offset0:138 offset1:203
	s_waitcnt lgkmcnt(1)
	v_cvt_pk_f16_f32 v6, v6, v7
	s_waitcnt lgkmcnt(0)
	v_cvt_pk_f16_f32 v7, v8, v9
	ds_read2_b32 v[8:9], v10 offset0:12 offset1:77
	ds_read2_b32 v[10:11], v10 offset0:142 offset1:207
	s_waitcnt lgkmcnt(1)
	v_cvt_pk_f16_f32 v8, v8, v9
	s_waitcnt lgkmcnt(0)
	v_cvt_pk_f16_f32 v9, v10, v11
	v_add_u32_e32 v10, s1, v12
	v_ashrrev_i32_e32 v11, 31, v10
	v_lshlrev_b64 v[10:11], 11, v[10:11]
	v_lshl_add_u64 v[10:11], s[2:3], 0, v[10:11]
	v_lshl_add_u64 v[10:11], v[10:11], 0, s[18:19]
	v_lshl_add_u64 v[10:11], v[10:11], 0, v[0:1]
	global_store_dwordx4 v[10:11], v[2:5], off
	global_store_dwordx4 v[10:11], v[6:9], off offset:16
	s_barrier
